# K-loop byte-phase pin: every 16-MFMA run starts at 4 mod 8
# speedup vs baseline: 1.0086x; 1.0017x over previous
.LBB0_228:
	ds_read_b128 v[128:131], v179
	ds_read_b128 v[132:135], v179 offset:1024
	ds_read_b128 v[136:139], v179 offset:2048
	ds_read_b128 v[140:143], v179 offset:3072
	ds_read_b128 v[162:165], v180
	ds_read_b128 v[166:169], v180 offset:1024
	ds_read_b128 v[170:173], v180 offset:2048
	ds_read_b128 v[186:189], v180 offset:3072
	s_add_u32 s8, s6, 0x10000
	s_addc_u32 s9, s7, 0
	s_cmp_eq_u32 s92, 12
	s_cselect_b32 s80, s69, s8
	s_cselect_b32 s81, s18, s9
	s_cselect_b32 s12, s77, vcc_lo
	s_cselect_b32 s13, s71, vcc_hi
	s_add_u32 s10, s80, 0x8000
	s_addc_u32 s11, s81, 0
	s_add_i32 m0, s79, 0xc000
	ds_read_b128 v[190:193], v181
	ds_read_b128 v[194:197], v181 offset:1024
	ds_read_b128 v[198:201], v181 offset:2048
	ds_read_b128 v[202:205], v181 offset:3072
	ds_read_b128 v[206:209], v181 offset:4096
	ds_read_b128 v[210:213], v181 offset:5120
	ds_read_b128 v[214:217], v181 offset:6144
	ds_read_b128 v[218:221], v181 offset:7168
	global_load_lds_dwordx4 v154, s[6:7]
	s_add_i32 m0, s79, 0xe000
	s_nop 0
	global_load_lds_dwordx4 v156, s[6:7]
	s_waitcnt vmcnt(8)
	s_waitcnt lgkmcnt(0)
	s_barrier
	s_setprio 1
	s_waitcnt lgkmcnt(0)
	v_mfma_f32_16x16x32_bf16 v[124:127], v[128:131], v[190:193], v[124:127]
	v_mfma_f32_16x16x32_bf16 v[120:123], v[136:139], v[190:193], v[120:123]
	v_mfma_f32_16x16x32_bf16 v[108:111], v[128:131], v[198:201], v[108:111]
	v_mfma_f32_16x16x32_bf16 v[104:107], v[136:139], v[198:201], v[104:107]
	v_mfma_f32_16x16x32_bf16 v[92:95], v[128:131], v[206:209], v[92:95]
	v_mfma_f32_16x16x32_bf16 v[88:91], v[136:139], v[206:209], v[88:91]
	v_mfma_f32_16x16x32_bf16 v[76:79], v[128:131], v[214:217], v[76:79]
	v_mfma_f32_16x16x32_bf16 v[72:75], v[136:139], v[214:217], v[72:75]
	v_mfma_f32_16x16x32_bf16 v[124:127], v[132:135], v[194:197], v[124:127]
	v_mfma_f32_16x16x32_bf16 v[120:123], v[140:143], v[194:197], v[120:123]
	v_mfma_f32_16x16x32_bf16 v[108:111], v[132:135], v[202:205], v[108:111]
	v_mfma_f32_16x16x32_bf16 v[104:107], v[140:143], v[202:205], v[104:107]
	v_mfma_f32_16x16x32_bf16 v[92:95], v[132:135], v[210:213], v[92:95]
	v_mfma_f32_16x16x32_bf16 v[88:91], v[140:143], v[210:213], v[88:91]
	v_mfma_f32_16x16x32_bf16 v[76:79], v[132:135], v[218:221], v[76:79]
	v_mfma_f32_16x16x32_bf16 v[72:75], v[140:143], v[218:221], v[72:75]
	s_setprio 0
	s_setprio 1
	v_mfma_f32_16x16x32_bf16 v[116:119], v[162:165], v[190:193], v[116:119]
	v_mfma_f32_16x16x32_bf16 v[112:115], v[170:173], v[190:193], v[112:115]
	v_mfma_f32_16x16x32_bf16 v[100:103], v[162:165], v[198:201], v[100:103]
	v_mfma_f32_16x16x32_bf16 v[96:99], v[170:173], v[198:201], v[96:99]
	v_mfma_f32_16x16x32_bf16 v[84:87], v[162:165], v[206:209], v[84:87]
	v_mfma_f32_16x16x32_bf16 v[80:83], v[170:173], v[206:209], v[80:83]
	v_mfma_f32_16x16x32_bf16 v[68:71], v[162:165], v[214:217], v[68:71]
	v_mfma_f32_16x16x32_bf16 v[64:67], v[170:173], v[214:217], v[64:67]
	v_mfma_f32_16x16x32_bf16 v[116:119], v[166:169], v[194:197], v[116:119]
	v_mfma_f32_16x16x32_bf16 v[112:115], v[186:189], v[194:197], v[112:115]
	v_mfma_f32_16x16x32_bf16 v[100:103], v[166:169], v[202:205], v[100:103]
	v_mfma_f32_16x16x32_bf16 v[96:99], v[186:189], v[202:205], v[96:99]
	v_mfma_f32_16x16x32_bf16 v[84:87], v[166:169], v[210:213], v[84:87]
	v_mfma_f32_16x16x32_bf16 v[80:83], v[186:189], v[210:213], v[80:83]
	v_mfma_f32_16x16x32_bf16 v[68:71], v[166:169], v[218:221], v[68:71]
	v_mfma_f32_16x16x32_bf16 v[64:67], v[186:189], v[218:221], v[64:67]
	s_setprio 0
	s_barrier
	s_add_i32 s6, s34, s84
	s_mov_b32 m0, s6
	ds_read_b128 v[190:193], v181 offset:16384
	ds_read_b128 v[194:197], v181 offset:17408
	ds_read_b128 v[198:201], v181 offset:18432
	ds_read_b128 v[202:205], v181 offset:19456
	ds_read_b128 v[206:209], v181 offset:20480
	ds_read_b128 v[210:213], v181 offset:21504
	ds_read_b128 v[214:217], v181 offset:22528
	ds_read_b128 v[218:221], v181 offset:23552
	global_load_lds_dwordx4 v146, s[12:13]
	s_add_i32 m0, s6, 0x2000
	s_add_u32 s6, s12, 0x40000
	s_addc_u32 s7, s13, 0
	s_add_i32 s38, s35, s84
	global_load_lds_dwordx4 v150, s[12:13]
	s_mov_b32 m0, s38
	s_nop 0
	global_load_lds_dwordx4 v146, s[6:7]
	s_add_i32 m0, s38, 0x2000
	s_nop 0
	global_load_lds_dwordx4 v150, s[6:7]
	s_mov_b32 m0, s79
	s_nop 0
	global_load_lds_dwordx4 v144, s[80:81]
	s_mov_b32 m0, s85
	s_nop 0
	global_load_lds_dwordx4 v148, s[80:81]
	s_waitcnt vmcnt(8)
	s_waitcnt lgkmcnt(0)
	s_barrier
	s_setprio 1
	s_waitcnt lgkmcnt(0)
	v_mfma_f32_16x16x32_bf16 v[60:63], v[128:131], v[190:193], v[60:63]
	v_mfma_f32_16x16x32_bf16 v[56:59], v[136:139], v[190:193], v[56:59]
	v_mfma_f32_16x16x32_bf16 v[44:47], v[128:131], v[198:201], v[44:47]
	v_mfma_f32_16x16x32_bf16 v[40:43], v[136:139], v[198:201], v[40:43]
	v_mfma_f32_16x16x32_bf16 v[28:31], v[128:131], v[206:209], v[28:31]
	v_mfma_f32_16x16x32_bf16 v[24:27], v[136:139], v[206:209], v[24:27]
	v_mfma_f32_16x16x32_bf16 v[12:15], v[128:131], v[214:217], v[12:15]
	v_mfma_f32_16x16x32_bf16 v[8:11], v[136:139], v[214:217], v[8:11]
	v_mfma_f32_16x16x32_bf16 v[60:63], v[132:135], v[194:197], v[60:63]
	v_mfma_f32_16x16x32_bf16 v[56:59], v[140:143], v[194:197], v[56:59]
	v_mfma_f32_16x16x32_bf16 v[44:47], v[132:135], v[202:205], v[44:47]
	v_mfma_f32_16x16x32_bf16 v[40:43], v[140:143], v[202:205], v[40:43]
	v_mfma_f32_16x16x32_bf16 v[28:31], v[132:135], v[210:213], v[28:31]
	v_mfma_f32_16x16x32_bf16 v[24:27], v[140:143], v[210:213], v[24:27]
	v_mfma_f32_16x16x32_bf16 v[12:15], v[132:135], v[218:221], v[12:15]
	v_mfma_f32_16x16x32_bf16 v[8:11], v[140:143], v[218:221], v[8:11]
	s_setprio 0
	s_setprio 1
	v_mfma_f32_16x16x32_bf16 v[52:55], v[162:165], v[190:193], v[52:55]
	v_mfma_f32_16x16x32_bf16 v[48:51], v[170:173], v[190:193], v[48:51]
	v_mfma_f32_16x16x32_bf16 v[36:39], v[162:165], v[198:201], v[36:39]
	v_mfma_f32_16x16x32_bf16 v[32:35], v[170:173], v[198:201], v[32:35]
	v_mfma_f32_16x16x32_bf16 v[20:23], v[162:165], v[206:209], v[20:23]
	v_mfma_f32_16x16x32_bf16 v[16:19], v[170:173], v[206:209], v[16:19]
	v_mfma_f32_16x16x32_bf16 v[4:7], v[162:165], v[214:217], v[4:7]
	v_mfma_f32_16x16x32_bf16 v[0:3], v[170:173], v[214:217], v[0:3]
	v_mfma_f32_16x16x32_bf16 v[52:55], v[166:169], v[194:197], v[52:55]
	v_mfma_f32_16x16x32_bf16 v[48:51], v[186:189], v[194:197], v[48:51]
	v_mfma_f32_16x16x32_bf16 v[36:39], v[166:169], v[202:205], v[36:39]
	v_mfma_f32_16x16x32_bf16 v[32:35], v[186:189], v[202:205], v[32:35]
	v_mfma_f32_16x16x32_bf16 v[20:23], v[166:169], v[210:213], v[20:23]
	v_mfma_f32_16x16x32_bf16 v[16:19], v[186:189], v[210:213], v[16:19]
	v_mfma_f32_16x16x32_bf16 v[4:7], v[166:169], v[218:221], v[4:7]
	v_mfma_f32_16x16x32_bf16 v[0:3], v[186:189], v[218:221], v[0:3]
	s_setprio 0
	s_barrier
	s_add_i32 s38, 0, 0x18000
	s_add_i32 s39, 0, 0x1c000
	v_add_u32_e32 v140, s38, v178
	v_add_u32_e32 v152, s39, v178
	ds_read_b128 v[128:131], v140
	ds_read_b128 v[132:135], v140 offset:1024
	ds_read_b128 v[136:139], v140 offset:2048
	ds_read_b128 v[140:143], v140 offset:3072
	ds_read_b128 v[162:165], v152
	ds_read_b128 v[166:169], v152 offset:1024
	ds_read_b128 v[170:173], v152 offset:2048
	ds_read_b128 v[186:189], v152 offset:3072
	s_add_u32 s6, s80, 0x4000
	s_addc_u32 s7, s81, 0
	s_mov_b32 m0, s86
	ds_read_b128 v[190:193], v181 offset:32768
	ds_read_b128 v[194:197], v181 offset:33792
	ds_read_b128 v[198:201], v181 offset:34816
	ds_read_b128 v[202:205], v181 offset:35840
	ds_read_b128 v[206:209], v181 offset:36864
	ds_read_b128 v[210:213], v181 offset:37888
	ds_read_b128 v[214:217], v181 offset:38912
	ds_read_b128 v[218:221], v181 offset:39936
	global_load_lds_dwordx4 v144, s[6:7]
	s_mov_b32 m0, s87
	s_nop 0
	global_load_lds_dwordx4 v148, s[6:7]
	s_nop 0
	s_waitcnt vmcnt(8)
	s_waitcnt lgkmcnt(0)
	s_barrier
	s_setprio 1
	s_waitcnt lgkmcnt(0)
	v_mfma_f32_16x16x32_bf16 v[124:127], v[128:131], v[190:193], v[124:127]
	v_mfma_f32_16x16x32_bf16 v[120:123], v[136:139], v[190:193], v[120:123]
	v_mfma_f32_16x16x32_bf16 v[108:111], v[128:131], v[198:201], v[108:111]
	v_mfma_f32_16x16x32_bf16 v[104:107], v[136:139], v[198:201], v[104:107]
	v_mfma_f32_16x16x32_bf16 v[92:95], v[128:131], v[206:209], v[92:95]
	v_mfma_f32_16x16x32_bf16 v[88:91], v[136:139], v[206:209], v[88:91]
	v_mfma_f32_16x16x32_bf16 v[76:79], v[128:131], v[214:217], v[76:79]
	v_mfma_f32_16x16x32_bf16 v[72:75], v[136:139], v[214:217], v[72:75]
	v_mfma_f32_16x16x32_bf16 v[124:127], v[132:135], v[194:197], v[124:127]
	v_mfma_f32_16x16x32_bf16 v[120:123], v[140:143], v[194:197], v[120:123]
	v_mfma_f32_16x16x32_bf16 v[108:111], v[132:135], v[202:205], v[108:111]
	v_mfma_f32_16x16x32_bf16 v[104:107], v[140:143], v[202:205], v[104:107]
	v_mfma_f32_16x16x32_bf16 v[92:95], v[132:135], v[210:213], v[92:95]
	v_mfma_f32_16x16x32_bf16 v[88:91], v[140:143], v[210:213], v[88:91]
	v_mfma_f32_16x16x32_bf16 v[76:79], v[132:135], v[218:221], v[76:79]
	v_mfma_f32_16x16x32_bf16 v[72:75], v[140:143], v[218:221], v[72:75]
	s_setprio 0
	s_setprio 1
	v_mfma_f32_16x16x32_bf16 v[116:119], v[162:165], v[190:193], v[116:119]
	v_mfma_f32_16x16x32_bf16 v[112:115], v[170:173], v[190:193], v[112:115]
	v_mfma_f32_16x16x32_bf16 v[100:103], v[162:165], v[198:201], v[100:103]
	v_mfma_f32_16x16x32_bf16 v[96:99], v[170:173], v[198:201], v[96:99]
	v_mfma_f32_16x16x32_bf16 v[84:87], v[162:165], v[206:209], v[84:87]
	v_mfma_f32_16x16x32_bf16 v[80:83], v[170:173], v[206:209], v[80:83]
	v_mfma_f32_16x16x32_bf16 v[68:71], v[162:165], v[214:217], v[68:71]
	v_mfma_f32_16x16x32_bf16 v[64:67], v[170:173], v[214:217], v[64:67]
	v_mfma_f32_16x16x32_bf16 v[116:119], v[166:169], v[194:197], v[116:119]
	v_mfma_f32_16x16x32_bf16 v[112:115], v[186:189], v[194:197], v[112:115]
	v_mfma_f32_16x16x32_bf16 v[100:103], v[166:169], v[202:205], v[100:103]
	v_mfma_f32_16x16x32_bf16 v[96:99], v[186:189], v[202:205], v[96:99]
	v_mfma_f32_16x16x32_bf16 v[84:87], v[166:169], v[210:213], v[84:87]
	v_mfma_f32_16x16x32_bf16 v[80:83], v[186:189], v[210:213], v[80:83]
	v_mfma_f32_16x16x32_bf16 v[68:71], v[166:169], v[218:221], v[68:71]
	v_mfma_f32_16x16x32_bf16 v[64:67], v[186:189], v[218:221], v[64:67]
	s_setprio 0
	s_barrier
	s_add_u32 s98, s12, s48
	s_addc_u32 s99, s13, s49
	s_add_i32 s6, s38, s84
	s_mov_b32 m0, s6
	ds_read_b128 v[190:193], v181 offset:49152
	ds_read_b128 v[194:197], v181 offset:50176
	ds_read_b128 v[198:201], v181 offset:51200
	ds_read_b128 v[202:205], v181 offset:52224
	ds_read_b128 v[206:209], v181 offset:53248
	ds_read_b128 v[210:213], v181 offset:54272
	ds_read_b128 v[214:217], v181 offset:55296
	ds_read_b128 v[218:221], v181 offset:56320
	global_load_lds_dwordx4 v146, s[98:99]
	s_add_i32 m0, s6, 0x2000
	s_add_u32 s6, s12, 0x40080
	s_addc_u32 s7, s13, 0
	s_add_i32 s12, s39, s84
	global_load_lds_dwordx4 v150, s[98:99]
	s_mov_b32 m0, s12
	s_nop 0
	global_load_lds_dwordx4 v146, s[6:7]
	s_add_i32 m0, s12, 0x2000
	s_nop 0
	global_load_lds_dwordx4 v150, s[6:7]
	s_mov_b32 m0, s33
	s_nop 0
	global_load_lds_dwordx4 v144, s[10:11]
	s_mov_b32 m0, s56
	s_nop 0
	global_load_lds_dwordx4 v148, s[10:11]
	s_waitcnt vmcnt(8)
	s_waitcnt lgkmcnt(0)
	s_barrier
	s_setprio 1
	s_waitcnt lgkmcnt(0)
	v_mfma_f32_16x16x32_bf16 v[60:63], v[128:131], v[190:193], v[60:63]
	v_mfma_f32_16x16x32_bf16 v[56:59], v[136:139], v[190:193], v[56:59]
	v_mfma_f32_16x16x32_bf16 v[44:47], v[128:131], v[198:201], v[44:47]
	v_mfma_f32_16x16x32_bf16 v[40:43], v[136:139], v[198:201], v[40:43]
	v_mfma_f32_16x16x32_bf16 v[28:31], v[128:131], v[206:209], v[28:31]
	v_mfma_f32_16x16x32_bf16 v[24:27], v[136:139], v[206:209], v[24:27]
	v_mfma_f32_16x16x32_bf16 v[12:15], v[128:131], v[214:217], v[12:15]
	v_mfma_f32_16x16x32_bf16 v[8:11], v[136:139], v[214:217], v[8:11]
	v_mfma_f32_16x16x32_bf16 v[60:63], v[132:135], v[194:197], v[60:63]
	v_mfma_f32_16x16x32_bf16 v[56:59], v[140:143], v[194:197], v[56:59]
	v_mfma_f32_16x16x32_bf16 v[44:47], v[132:135], v[202:205], v[44:47]
	v_mfma_f32_16x16x32_bf16 v[40:43], v[140:143], v[202:205], v[40:43]
	v_mfma_f32_16x16x32_bf16 v[28:31], v[132:135], v[210:213], v[28:31]
	v_mfma_f32_16x16x32_bf16 v[24:27], v[140:143], v[210:213], v[24:27]
	v_mfma_f32_16x16x32_bf16 v[12:15], v[132:135], v[218:221], v[12:15]
	v_mfma_f32_16x16x32_bf16 v[8:11], v[140:143], v[218:221], v[8:11]
	s_setprio 0
	s_setprio 1
	v_mfma_f32_16x16x32_bf16 v[52:55], v[162:165], v[190:193], v[52:55]
	v_mfma_f32_16x16x32_bf16 v[48:51], v[170:173], v[190:193], v[48:51]
	v_mfma_f32_16x16x32_bf16 v[36:39], v[162:165], v[198:201], v[36:39]
	v_mfma_f32_16x16x32_bf16 v[32:35], v[170:173], v[198:201], v[32:35]
	v_mfma_f32_16x16x32_bf16 v[20:23], v[162:165], v[206:209], v[20:23]
	v_mfma_f32_16x16x32_bf16 v[16:19], v[170:173], v[206:209], v[16:19]
	v_mfma_f32_16x16x32_bf16 v[4:7], v[162:165], v[214:217], v[4:7]
	v_mfma_f32_16x16x32_bf16 v[0:3], v[170:173], v[214:217], v[0:3]
	v_mfma_f32_16x16x32_bf16 v[52:55], v[166:169], v[194:197], v[52:55]
	v_mfma_f32_16x16x32_bf16 v[48:51], v[186:189], v[194:197], v[48:51]
	v_mfma_f32_16x16x32_bf16 v[36:39], v[166:169], v[202:205], v[36:39]
	v_mfma_f32_16x16x32_bf16 v[32:35], v[186:189], v[202:205], v[32:35]
	v_mfma_f32_16x16x32_bf16 v[20:23], v[166:169], v[210:213], v[20:23]
	v_mfma_f32_16x16x32_bf16 v[16:19], v[186:189], v[210:213], v[16:19]
	v_mfma_f32_16x16x32_bf16 v[4:7], v[166:169], v[218:221], v[4:7]
	v_mfma_f32_16x16x32_bf16 v[0:3], v[186:189], v[218:221], v[0:3]
	s_setprio 0
	s_barrier
	s_add_i32 s92, s92, 2
	s_add_u32 vcc_lo, vcc_lo, 0x100
	s_addc_u32 vcc_hi, vcc_hi, 0
	s_cmp_gt_u32 s92, 13
	s_mov_b64 s[6:7], s[8:9]
	s_cbranch_scc0 .LBB0_228
	s_and_b64 vcc, exec, s[82:83]
	s_cbranch_vccz .LBB0_231
	s_barrier
